# fft3 loop as well: prefetch waited after the tile MFMAs, before its 64 short stores; head vmcnt ladder removed
# baseline (speedup 1.0000x reference)
.LBB0_821:
	s_or_b64 exec, exec, s[0:1]
	s_cmpk_lt_i32 s2, 0x840
	s_waitcnt lgkmcnt(0)
	s_barrier
	s_cbranch_scc0 .LBB0_842
	v_lshrrev_b32_e32 v82, 4, v6
	v_and_b32_e32 v7, 48, v82
	v_lshrrev_b32_e32 v8, 3, v6
	v_lshlrev_b32_e32 v9, 3, v6
	v_and_or_b32 v7, v8, 8, v7
	v_lshrrev_b32_e32 v5, 5, v6
	v_lshrrev_b32_e32 v7, 1, v7
	v_bfe_u32 v8, v9, 5, 2
	v_bfe_u32 v12, v6, 4, 2
	v_or_b32_e32 v7, v7, v8
	v_and_or_b32 v5, v5, 4, v12
	v_lshlrev_b32_e32 v12, 4, v6
	v_lshlrev_b32_e32 v7, 9, v7
	v_lshlrev_b32_e32 v5, 6, v5
	v_and_b32_e32 v13, 48, v12
	v_add_u32_e32 v84, 32, v82
	v_or3_b32 v92, v7, v5, v13
	v_and_b32_e32 v7, 0x70, v84
	v_lshlrev_b32_e32 v14, 1, v84
	v_and_or_b32 v7, v14, 8, v7
	v_lshrrev_b32_e32 v2, 2, v6
	v_lshrrev_b32_e32 v7, 1, v7
	v_bfe_u32 v3, v6, 5, 1
	v_and_b32_e32 v4, 48, v2
	v_or_b32_e32 v7, v7, v8
	v_and_or_b32 v2, v6, 15, v4
	v_lshlrev_b32_e32 v11, 3, v3
	v_lshlrev_b32_e32 v7, 9, v7
	v_and_b32_e32 v83, 31, v6
	v_lshlrev_b32_e32 v10, 6, v2
	v_or3_b32 v93, v7, v5, v13
	v_and_b32_e32 v7, 0xc0, v12
	v_or_b32_e32 v12, 0x70, v11
	s_movk_i32 s0, 0xc00
	v_mul_u32_u24_e32 v13, v10, v12
	v_mad_u32_u24 v14, v10, v12, s0
	v_cmp_gt_u32_e32 vcc, 16, v83
	v_mad_u32_u24 v12, v10, v12, v10
	s_mov_b32 s0, 0x3e000000
	v_cndmask_b32_e32 v13, v13, v14, vcc
	v_add_u32_e32 v14, 0xc00, v12
	v_cndmask_b32_e32 v14, v12, v14, vcc
	v_add_u32_e32 v12, v12, v10
	v_add_u32_e32 v15, 0xc00, v12
	v_cndmask_b32_e32 v15, v12, v15, vcc
	v_add_u32_e32 v12, v12, v10
	v_add_u32_e32 v16, 0xc00, v12
	v_cndmask_b32_e32 v16, v12, v16, vcc
	v_add_u32_e32 v12, v12, v10
	v_add_u32_e32 v17, 0xc00, v12
	v_cndmask_b32_e32 v17, v12, v17, vcc
	v_add_u32_e32 v12, v12, v10
	v_add_u32_e32 v18, 0xc00, v12
	v_cndmask_b32_e32 v18, v12, v18, vcc
	v_add_u32_e32 v12, v12, v10
	v_add_u32_e32 v19, 0xc00, v12
	v_add_u32_e32 v20, v12, v10
	v_cndmask_b32_e32 v19, v12, v19, vcc
	v_add_u32_e32 v12, 0xc00, v20
	v_and_b32_e32 v13, 0xe00, v13
	v_and_b32_e32 v14, 0xfc0, v14
	v_and_b32_e32 v15, 0xf80, v15
	v_and_b32_e32 v16, 0xfc0, v16
	v_and_b32_e32 v17, 0xf00, v17
	v_and_b32_e32 v18, 0xfc0, v18
	v_and_b32_e32 v19, 0xf80, v19
	v_cndmask_b32_e32 v12, v20, v12, vcc
	v_lshl_add_u32 v13, v13, 2, s12
	v_lshl_add_u32 v14, v14, 2, s12
	v_lshl_add_u32 v15, v15, 2, s12
	v_lshl_add_u32 v16, v16, 2, s12
	v_lshl_add_u32 v17, v17, 2, s12
	v_lshl_add_u32 v18, v18, 2, s12
	v_lshl_add_u32 v19, v19, 2, s12
	v_and_b32_e32 v12, 0xfc0, v12
	v_lshl_add_u32 v21, v12, 2, s12
	ds_read_b32 v12, v13
	ds_read_b32 v13, v14
	ds_read_b32 v14, v15
	ds_read_b32 v15, v16
	ds_read_b32 v16, v17
	ds_read_b32 v17, v18
	ds_read_b32 v18, v19
	ds_read_b32 v19, v21
	s_waitcnt lgkmcnt(6)
	v_pk_mul_f32 v[12:13], v[12:13], s[0:1] op_sel_hi:[1,0]
	s_add_u32 s6, s56, 0x16cb0000
	v_cvt_pk_bf16_f32 v34, v12, v13
	s_waitcnt lgkmcnt(4)
	v_pk_mul_f32 v[12:13], v[14:15], s[0:1] op_sel_hi:[1,0]
	s_addc_u32 s7, s57, 0
	v_cvt_pk_bf16_f32 v35, v12, v13
	s_waitcnt lgkmcnt(2)
	v_pk_mul_f32 v[12:13], v[16:17], s[0:1] op_sel_hi:[1,0]
	s_add_u32 s8, s56, 0xecb0000
	v_cvt_pk_bf16_f32 v36, v12, v13
	s_waitcnt lgkmcnt(0)
	v_pk_mul_f32 v[12:13], v[18:19], s[0:1] op_sel_hi:[1,0]
	s_movk_i32 s1, 0xffe9
	v_cvt_pk_bf16_f32 v37, v12, v13
	v_mad_i32_i24 v12, v10, s1, v20
	v_add_u32_e32 v13, 0xc00, v12
	v_cndmask_b32_e32 v13, v12, v13, vcc
	v_add_u32_e32 v12, v12, v10
	v_add_u32_e32 v14, 0xc00, v12
	v_cndmask_b32_e32 v14, v12, v14, vcc
	v_add_u32_e32 v12, v12, v10
	v_add_u32_e32 v15, 0xc00, v12
	v_cndmask_b32_e32 v15, v12, v15, vcc
	v_add_u32_e32 v12, v12, v10
	v_add_u32_e32 v16, 0xc00, v12
	v_cndmask_b32_e32 v16, v12, v16, vcc
	v_add_u32_e32 v12, v12, v10
	v_add_u32_e32 v17, 0xc00, v12
	v_cndmask_b32_e32 v17, v12, v17, vcc
	v_add_u32_e32 v12, v12, v10
	v_add_u32_e32 v18, 0xc00, v12
	v_cndmask_b32_e32 v18, v12, v18, vcc
	v_add_u32_e32 v12, v12, v10
	v_add_u32_e32 v19, 0xc00, v12
	v_add_u32_e32 v20, v12, v10
	v_cndmask_b32_e32 v19, v12, v19, vcc
	v_add_u32_e32 v12, 0xc00, v20
	v_and_b32_e32 v13, 0xe00, v13
	v_and_b32_e32 v14, 0xfc0, v14
	v_and_b32_e32 v15, 0xf80, v15
	v_and_b32_e32 v16, 0xfc0, v16
	v_and_b32_e32 v17, 0xf00, v17
	v_and_b32_e32 v18, 0xfc0, v18
	v_and_b32_e32 v19, 0xf80, v19
	v_cndmask_b32_e32 v12, v20, v12, vcc
	v_lshl_add_u32 v13, v13, 2, s12
	v_lshl_add_u32 v14, v14, 2, s12
	v_lshl_add_u32 v15, v15, 2, s12
	v_lshl_add_u32 v16, v16, 2, s12
	v_lshl_add_u32 v17, v17, 2, s12
	v_lshl_add_u32 v18, v18, 2, s12
	v_lshl_add_u32 v19, v19, 2, s12
	v_and_b32_e32 v12, 0xfc0, v12
	v_lshl_add_u32 v21, v12, 2, s12
	ds_read_b32 v12, v13
	ds_read_b32 v13, v14
	ds_read_b32 v14, v15
	ds_read_b32 v15, v16
	ds_read_b32 v16, v17
	ds_read_b32 v17, v18
	ds_read_b32 v18, v19
	ds_read_b32 v19, v21
	s_waitcnt lgkmcnt(6)
	v_pk_mul_f32 v[12:13], v[12:13], s[0:1] op_sel_hi:[1,0]
	s_addc_u32 s9, s57, 0
	v_cvt_pk_bf16_f32 v38, v12, v13
	s_waitcnt lgkmcnt(4)
	v_pk_mul_f32 v[12:13], v[14:15], s[0:1] op_sel_hi:[1,0]
	v_and_b32_e32 v2, 0x78, v9
	v_cvt_pk_bf16_f32 v39, v12, v13
	s_waitcnt lgkmcnt(2)
	v_pk_mul_f32 v[12:13], v[16:17], s[0:1] op_sel_hi:[1,0]
	s_mov_b32 s11, 0
	v_cvt_pk_bf16_f32 v40, v12, v13
	s_waitcnt lgkmcnt(0)
	v_pk_mul_f32 v[12:13], v[18:19], s[0:1] op_sel_hi:[1,0]
	v_mov_b32_e32 v87, 0
	v_cvt_pk_bf16_f32 v41, v12, v13
	v_mad_i32_i24 v12, v10, s1, v20
	v_add_u32_e32 v13, 0xc00, v12
	v_cndmask_b32_e32 v13, v12, v13, vcc
	v_add_u32_e32 v12, v12, v10
	v_add_u32_e32 v14, 0xc00, v12
	v_cndmask_b32_e32 v14, v12, v14, vcc
	v_add_u32_e32 v12, v12, v10
	v_add_u32_e32 v15, 0xc00, v12
	v_cndmask_b32_e32 v15, v12, v15, vcc
	v_add_u32_e32 v12, v12, v10
	v_add_u32_e32 v16, 0xc00, v12
	v_cndmask_b32_e32 v16, v12, v16, vcc
	v_add_u32_e32 v12, v12, v10
	v_add_u32_e32 v17, 0xc00, v12
	v_cndmask_b32_e32 v17, v12, v17, vcc
	v_add_u32_e32 v12, v12, v10
	v_add_u32_e32 v18, 0xc00, v12
	v_cndmask_b32_e32 v18, v12, v18, vcc
	v_add_u32_e32 v12, v12, v10
	v_add_u32_e32 v19, 0xc00, v12
	v_add_u32_e32 v20, v12, v10
	v_cndmask_b32_e32 v19, v12, v19, vcc
	v_add_u32_e32 v12, 0xc00, v20
	v_and_b32_e32 v13, 0xe00, v13
	v_and_b32_e32 v14, 0xfc0, v14
	v_and_b32_e32 v15, 0xf80, v15
	v_and_b32_e32 v16, 0xfc0, v16
	v_and_b32_e32 v17, 0xf00, v17
	v_and_b32_e32 v18, 0xfc0, v18
	v_and_b32_e32 v19, 0xf80, v19
	v_cndmask_b32_e32 v12, v20, v12, vcc
	v_lshl_add_u32 v13, v13, 2, s12
	v_lshl_add_u32 v14, v14, 2, s12
	v_lshl_add_u32 v15, v15, 2, s12
	v_lshl_add_u32 v16, v16, 2, s12
	v_lshl_add_u32 v17, v17, 2, s12
	v_lshl_add_u32 v18, v18, 2, s12
	v_lshl_add_u32 v19, v19, 2, s12
	v_and_b32_e32 v12, 0xfc0, v12
	v_lshl_add_u32 v21, v12, 2, s12
	ds_read_b32 v12, v13
	ds_read_b32 v13, v14
	ds_read_b32 v14, v15
	ds_read_b32 v15, v16
	ds_read_b32 v16, v17
	ds_read_b32 v17, v18
	ds_read_b32 v18, v19
	ds_read_b32 v19, v21
	s_waitcnt lgkmcnt(6)
	v_pk_mul_f32 v[12:13], v[12:13], s[0:1] op_sel_hi:[1,0]
	v_lshlrev_b32_e32 v86, 1, v2
	v_cvt_pk_bf16_f32 v42, v12, v13
	s_waitcnt lgkmcnt(4)
	v_pk_mul_f32 v[12:13], v[14:15], s[0:1] op_sel_hi:[1,0]
	v_mov_b32_e32 v85, v87
	v_cvt_pk_bf16_f32 v43, v12, v13
	s_waitcnt lgkmcnt(2)
	v_pk_mul_f32 v[12:13], v[16:17], s[0:1] op_sel_hi:[1,0]
	s_movk_i32 s13, 0x400
	v_cvt_pk_bf16_f32 v44, v12, v13
	s_waitcnt lgkmcnt(0)
	v_pk_mul_f32 v[12:13], v[18:19], s[0:1] op_sel_hi:[1,0]
	s_lshl_b32 s16, s2, 7
	v_cvt_pk_bf16_f32 v45, v12, v13
	v_mad_i32_i24 v12, v10, s1, v20
	v_add_u32_e32 v13, 0xc00, v12
	v_cndmask_b32_e32 v13, v12, v13, vcc
	v_add_u32_e32 v12, v12, v10
	v_add_u32_e32 v14, 0xc00, v12
	v_cndmask_b32_e32 v14, v12, v14, vcc
	v_add_u32_e32 v12, v12, v10
	v_add_u32_e32 v15, 0xc00, v12
	v_cndmask_b32_e32 v15, v12, v15, vcc
	v_add_u32_e32 v12, v12, v10
	v_add_u32_e32 v16, 0xc00, v12
	v_cndmask_b32_e32 v16, v12, v16, vcc
	v_add_u32_e32 v12, v12, v10
	v_add_u32_e32 v17, 0xc00, v12
	v_cndmask_b32_e32 v17, v12, v17, vcc
	v_add_u32_e32 v12, v12, v10
	v_add_u32_e32 v18, 0xc00, v12
	v_cndmask_b32_e32 v18, v12, v18, vcc
	v_add_u32_e32 v12, v12, v10
	v_add_u32_e32 v19, 0xc00, v12
	v_add_u32_e32 v20, v12, v10
	v_cndmask_b32_e32 v19, v12, v19, vcc
	v_add_u32_e32 v12, 0xc00, v20
	v_and_b32_e32 v13, 0xe00, v13
	v_and_b32_e32 v14, 0xfc0, v14
	v_and_b32_e32 v15, 0xf80, v15
	v_and_b32_e32 v16, 0xfc0, v16
	v_and_b32_e32 v17, 0xf00, v17
	v_and_b32_e32 v18, 0xfc0, v18
	v_and_b32_e32 v19, 0xf80, v19
	v_cndmask_b32_e32 v12, v20, v12, vcc
	v_lshl_add_u32 v13, v13, 2, s12
	v_lshl_add_u32 v14, v14, 2, s12
	v_lshl_add_u32 v15, v15, 2, s12
	v_lshl_add_u32 v16, v16, 2, s12
	v_lshl_add_u32 v17, v17, 2, s12
	v_lshl_add_u32 v18, v18, 2, s12
	v_lshl_add_u32 v19, v19, 2, s12
	v_and_b32_e32 v12, 0xfc0, v12
	v_lshl_add_u32 v21, v12, 2, s12
	ds_read_b32 v12, v13
	ds_read_b32 v13, v14
	ds_read_b32 v14, v15
	ds_read_b32 v15, v16
	ds_read_b32 v16, v17
	ds_read_b32 v17, v18
	ds_read_b32 v18, v19
	ds_read_b32 v19, v21
	s_waitcnt lgkmcnt(6)
	v_pk_mul_f32 v[12:13], v[12:13], s[0:1] op_sel_hi:[1,0]
	v_lshrrev_b32_e32 v8, 8, v6
	v_cvt_pk_bf16_f32 v46, v12, v13
	s_waitcnt lgkmcnt(4)
	v_pk_mul_f32 v[12:13], v[14:15], s[0:1] op_sel_hi:[1,0]
	v_lshlrev_b32_e32 v5, 10, v8
	v_cvt_pk_bf16_f32 v47, v12, v13
	s_waitcnt lgkmcnt(2)
	v_pk_mul_f32 v[12:13], v[16:17], s[0:1] op_sel_hi:[1,0]
	v_lshlrev_b32_e32 v6, 1, v6
	v_cvt_pk_bf16_f32 v48, v12, v13
	s_waitcnt lgkmcnt(0)
	v_pk_mul_f32 v[12:13], v[18:19], s[0:1] op_sel_hi:[1,0]
	v_lshlrev_b32_e32 v4, 6, v4
	v_cvt_pk_bf16_f32 v49, v12, v13
	v_mad_i32_i24 v12, v10, s1, v20
	v_add_u32_e32 v13, 0x400, v12
	v_cndmask_b32_e32 v13, v13, v12, vcc
	v_add_u32_e32 v12, v12, v10
	v_add_u32_e32 v14, 0x400, v12
	v_cndmask_b32_e32 v14, v14, v12, vcc
	v_add_u32_e32 v12, v12, v10
	v_add_u32_e32 v15, 0x400, v12
	v_cndmask_b32_e32 v15, v15, v12, vcc
	v_add_u32_e32 v12, v12, v10
	v_add_u32_e32 v16, 0x400, v12
	v_cndmask_b32_e32 v16, v16, v12, vcc
	v_add_u32_e32 v12, v12, v10
	v_add_u32_e32 v17, 0x400, v12
	v_cndmask_b32_e32 v17, v17, v12, vcc
	v_add_u32_e32 v12, v12, v10
	v_add_u32_e32 v18, 0x400, v12
	v_cndmask_b32_e32 v18, v18, v12, vcc
	v_add_u32_e32 v12, v12, v10
	v_add_u32_e32 v19, 0x400, v12
	v_add_u32_e32 v20, v12, v10
	v_cndmask_b32_e32 v19, v19, v12, vcc
	v_add_u32_e32 v12, 0x400, v20
	v_and_b32_e32 v13, 0xe00, v13
	v_and_b32_e32 v14, 0xfc0, v14
	v_and_b32_e32 v15, 0xf80, v15
	v_and_b32_e32 v16, 0xfc0, v16
	v_and_b32_e32 v17, 0xf00, v17
	v_and_b32_e32 v18, 0xfc0, v18
	v_and_b32_e32 v19, 0xf80, v19
	v_cndmask_b32_e32 v12, v12, v20, vcc
	v_lshl_add_u32 v13, v13, 2, s12
	v_lshl_add_u32 v14, v14, 2, s12
	v_lshl_add_u32 v15, v15, 2, s12
	v_lshl_add_u32 v16, v16, 2, s12
	v_lshl_add_u32 v17, v17, 2, s12
	v_lshl_add_u32 v18, v18, 2, s12
	v_lshl_add_u32 v19, v19, 2, s12
	v_and_b32_e32 v12, 0xfc0, v12
	v_lshl_add_u32 v21, v12, 2, s12
	ds_read_b32 v12, v13
	ds_read_b32 v13, v14
	ds_read_b32 v14, v15
	ds_read_b32 v15, v16
	ds_read_b32 v16, v17
	ds_read_b32 v17, v18
	ds_read_b32 v18, v19
	ds_read_b32 v19, v21
	s_waitcnt lgkmcnt(6)
	v_pk_mul_f32 v[12:13], v[12:13], s[0:1] op_sel_hi:[1,0]
	v_and_b32_e32 v6, 32, v6
	v_cvt_pk_bf16_f32 v50, v12, v13
	s_waitcnt lgkmcnt(4)
	v_pk_mul_f32 v[12:13], v[14:15], s[0:1] op_sel_hi:[1,0]
	v_and_b32_e32 v9, 0x118, v9
	v_cvt_pk_bf16_f32 v51, v12, v13
	s_waitcnt lgkmcnt(2)
	v_pk_mul_f32 v[12:13], v[16:17], s[0:1] op_sel_hi:[1,0]
	v_lshl_or_b32 v95, v3, 8, v4
	v_cvt_pk_bf16_f32 v52, v12, v13
	s_waitcnt lgkmcnt(0)
	v_pk_mul_f32 v[12:13], v[18:19], s[0:1] op_sel_hi:[1,0]
	s_movk_i32 s3, 0xc0
	v_cvt_pk_bf16_f32 v53, v12, v13
	v_mad_i32_i24 v12, v10, s1, v20
	v_add_u32_e32 v13, 0x400, v12
	v_cndmask_b32_e32 v13, v13, v12, vcc
	v_add_u32_e32 v12, v12, v10
	v_add_u32_e32 v14, 0x400, v12
	v_cndmask_b32_e32 v14, v14, v12, vcc
	v_add_u32_e32 v12, v12, v10
	v_add_u32_e32 v15, 0x400, v12
	v_cndmask_b32_e32 v15, v15, v12, vcc
	v_add_u32_e32 v12, v12, v10
	v_add_u32_e32 v16, 0x400, v12
	v_cndmask_b32_e32 v16, v16, v12, vcc
	v_add_u32_e32 v12, v12, v10
	v_add_u32_e32 v17, 0x400, v12
	v_cndmask_b32_e32 v17, v17, v12, vcc
	v_add_u32_e32 v12, v12, v10
	v_add_u32_e32 v18, 0x400, v12
	v_cndmask_b32_e32 v18, v18, v12, vcc
	v_add_u32_e32 v12, v12, v10
	v_add_u32_e32 v19, 0x400, v12
	v_add_u32_e32 v20, v12, v10
	v_cndmask_b32_e32 v19, v19, v12, vcc
	v_add_u32_e32 v12, 0x400, v20
	v_and_b32_e32 v13, 0xe00, v13
	v_and_b32_e32 v14, 0xfc0, v14
	v_and_b32_e32 v15, 0xf80, v15
	v_and_b32_e32 v16, 0xfc0, v16
	v_and_b32_e32 v17, 0xf00, v17
	v_and_b32_e32 v18, 0xfc0, v18
	v_and_b32_e32 v19, 0xf80, v19
	v_cndmask_b32_e32 v12, v12, v20, vcc
	v_lshl_add_u32 v13, v13, 2, s12
	v_lshl_add_u32 v14, v14, 2, s12
	v_lshl_add_u32 v15, v15, 2, s12
	v_lshl_add_u32 v16, v16, 2, s12
	v_lshl_add_u32 v17, v17, 2, s12
	v_lshl_add_u32 v18, v18, 2, s12
	v_lshl_add_u32 v19, v19, 2, s12
	v_and_b32_e32 v12, 0xfc0, v12
	v_lshl_add_u32 v21, v12, 2, s12
	ds_read_b32 v12, v13
	ds_read_b32 v13, v14
	ds_read_b32 v14, v15
	ds_read_b32 v15, v16
	ds_read_b32 v16, v17
	ds_read_b32 v17, v18
	ds_read_b32 v18, v19
	ds_read_b32 v19, v21
	s_waitcnt lgkmcnt(6)
	v_pk_mul_f32 v[12:13], v[12:13], s[0:1] op_sel_hi:[1,0]
	v_lshlrev_b32_e32 v94, 6, v8
	v_cvt_pk_bf16_f32 v54, v12, v13
	s_waitcnt lgkmcnt(4)
	v_pk_mul_f32 v[12:13], v[14:15], s[0:1] op_sel_hi:[1,0]
	v_or_b32_e32 v96, 64, v95
	v_cvt_pk_bf16_f32 v55, v12, v13
	s_waitcnt lgkmcnt(2)
	v_pk_mul_f32 v[12:13], v[16:17], s[0:1] op_sel_hi:[1,0]
	v_or_b32_e32 v97, 0x80, v95
	v_cvt_pk_bf16_f32 v56, v12, v13
	s_waitcnt lgkmcnt(0)
	v_pk_mul_f32 v[12:13], v[18:19], s[0:1] op_sel_hi:[1,0]
	v_or_b32_e32 v98, 0xc0, v95
	v_cvt_pk_bf16_f32 v57, v12, v13
	v_mad_i32_i24 v12, v10, s1, v20
	v_add_u32_e32 v13, 0x400, v12
	v_cndmask_b32_e32 v13, v13, v12, vcc
	v_add_u32_e32 v12, v12, v10
	v_add_u32_e32 v14, 0x400, v12
	v_cndmask_b32_e32 v14, v14, v12, vcc
	v_add_u32_e32 v12, v12, v10
	v_add_u32_e32 v15, 0x400, v12
	v_cndmask_b32_e32 v15, v15, v12, vcc
	v_add_u32_e32 v12, v12, v10
	v_add_u32_e32 v16, 0x400, v12
	v_cndmask_b32_e32 v16, v16, v12, vcc
	v_add_u32_e32 v12, v12, v10
	v_add_u32_e32 v17, 0x400, v12
	v_cndmask_b32_e32 v17, v17, v12, vcc
	v_add_u32_e32 v12, v12, v10
	v_add_u32_e32 v18, 0x400, v12
	v_cndmask_b32_e32 v18, v18, v12, vcc
	v_add_u32_e32 v12, v12, v10
	v_add_u32_e32 v19, 0x400, v12
	v_cndmask_b32_e32 v19, v19, v12, vcc
	v_add_u32_e32 v12, v12, v10
	v_add_u32_e32 v20, 0x400, v12
	v_and_b32_e32 v13, 0xe00, v13
	v_and_b32_e32 v14, 0xfc0, v14
	v_and_b32_e32 v15, 0xf80, v15
	v_and_b32_e32 v16, 0xfc0, v16
	v_and_b32_e32 v17, 0xf00, v17
	v_and_b32_e32 v18, 0xfc0, v18
	v_and_b32_e32 v19, 0xf80, v19
	v_cndmask_b32_e32 v12, v20, v12, vcc
	v_lshl_add_u32 v13, v13, 2, s12
	v_lshl_add_u32 v14, v14, 2, s12
	v_lshl_add_u32 v15, v15, 2, s12
	v_lshl_add_u32 v16, v16, 2, s12
	v_lshl_add_u32 v17, v17, 2, s12
	v_lshl_add_u32 v18, v18, 2, s12
	v_lshl_add_u32 v19, v19, 2, s12
	v_and_b32_e32 v12, 0xfc0, v12
	v_lshl_add_u32 v20, v12, 2, s12
	ds_read_b32 v12, v13
	ds_read_b32 v13, v14
	ds_read_b32 v14, v15
	ds_read_b32 v15, v16
	ds_read_b32 v16, v17
	ds_read_b32 v17, v18
	ds_read_b32 v18, v19
	ds_read_b32 v19, v20
	s_waitcnt lgkmcnt(6)
	v_pk_mul_f32 v[12:13], v[12:13], s[0:1] op_sel_hi:[1,0]
	v_or_b32_e32 v99, 0x200, v95
	v_cvt_pk_bf16_f32 v58, v12, v13
	s_waitcnt lgkmcnt(4)
	v_pk_mul_f32 v[12:13], v[14:15], s[0:1] op_sel_hi:[1,0]
	v_or_b32_e32 v100, 0x240, v95
	v_cvt_pk_bf16_f32 v59, v12, v13
	s_waitcnt lgkmcnt(2)
	v_pk_mul_f32 v[12:13], v[16:17], s[0:1] op_sel_hi:[1,0]
	s_ashr_i32 s1, s2, 3
	s_mul_hi_i32 s10, s1, 0x3e0f83e1
	s_lshr_b32 s14, s10, 31
	s_ashr_i32 s10, s10, 3
	s_add_i32 s10, s10, s14
	s_mul_i32 s10, s10, 31
	s_add_i32 s14, s10, s1
	s_ashr_i32 s15, s14, 31
	s_lshl_b64 s[14:15], s[14:15], 7
	v_or_b32_e32 v14, s14, v82
	v_mov_b32_e32 v15, s15
	v_lshlrev_b64 v[16:17], 11, v[14:15]
	s_lshl_b32 s1, s2, 8
	v_or_b32_e32 v14, s14, v84
	v_lshl_add_u64 v[16:17], s[8:9], 0, v[16:17]
	s_and_b32 s10, s1, 0x700
	v_lshlrev_b64 v[20:21], 11, v[14:15]
	v_lshl_add_u64 v[16:17], v[16:17], 0, s[10:11]
	v_lshl_add_u64 v[20:21], s[8:9], 0, v[20:21]
	s_or_b32 s14, s14, 64
	v_lshl_add_u64 v[16:17], v[16:17], 0, v[86:87]
	v_lshl_add_u64 v[20:21], v[20:21], 0, s[10:11]
	v_or_b32_e32 v14, s14, v82
	v_lshl_add_u64 v[20:21], v[20:21], 0, v[86:87]
	global_load_dwordx4 v[62:65], v[16:17], off
	global_load_dwordx4 v[66:69], v[20:21], off
	v_lshlrev_b64 v[14:15], 11, v[14:15]
	v_lshl_add_u64 v[16:17], s[14:15], 0, v[84:85]
	v_lshl_add_u64 v[14:15], s[8:9], 0, v[14:15]
	v_lshlrev_b64 v[16:17], 11, v[16:17]
	v_lshl_add_u64 v[14:15], v[14:15], 0, s[10:11]
	v_lshl_add_u64 v[16:17], s[8:9], 0, v[16:17]
	v_lshl_add_u64 v[14:15], v[14:15], 0, v[86:87]
	v_lshl_add_u64 v[16:17], v[16:17], 0, s[10:11]
	v_lshl_add_u64 v[16:17], v[16:17], 0, v[86:87]
	global_load_dwordx4 v[74:77], v[14:15], off
	global_load_dwordx4 v[78:81], v[16:17], off
	v_cvt_pk_bf16_f32 v60, v12, v13
	s_waitcnt lgkmcnt(0)
	v_pk_mul_f32 v[12:13], v[18:19], s[0:1] op_sel_hi:[1,0]
	s_cmp_lg_u32 0, -1
	v_cvt_pk_bf16_f32 v61, v12, v13
	v_mul_u32_u24_e32 v12, v10, v11
	v_mad_u32_u24 v13, v10, v11, s13
	v_mad_u32_u24 v11, v10, v11, v10
	v_cndmask_b32_e32 v12, v13, v12, vcc
	v_add_u32_e32 v13, 0x400, v11
	v_cndmask_b32_e32 v13, v13, v11, vcc
	v_add_u32_e32 v11, v11, v10
	v_add_u32_e32 v14, 0x400, v11
	v_cndmask_b32_e32 v14, v14, v11, vcc
	v_add_u32_e32 v11, v11, v10
	v_add_u32_e32 v15, 0x400, v11
	v_cndmask_b32_e32 v15, v15, v11, vcc
	v_add_u32_e32 v11, v11, v10
	v_add_u32_e32 v16, 0x400, v11
	v_cndmask_b32_e32 v16, v16, v11, vcc
	v_add_u32_e32 v11, v11, v10
	v_add_u32_e32 v17, 0x400, v11
	v_cndmask_b32_e32 v17, v17, v11, vcc
	v_add_u32_e32 v11, v11, v10
	v_add_u32_e32 v18, 0x400, v11
	v_add_u32_e32 v10, v11, v10
	v_cndmask_b32_e32 v18, v18, v11, vcc
	v_add_u32_e32 v11, 0x400, v10
	v_and_b32_e32 v12, 0xe00, v12
	v_and_b32_e32 v13, 0xfc0, v13
	v_and_b32_e32 v14, 0xf80, v14
	v_and_b32_e32 v15, 0xfc0, v15
	v_and_b32_e32 v16, 0xf00, v16
	v_and_b32_e32 v17, 0xfc0, v17
	v_cndmask_b32_e32 v10, v11, v10, vcc
	v_lshl_add_u32 v12, v12, 2, s12
	v_lshl_add_u32 v13, v13, 2, s12
	v_lshl_add_u32 v14, v14, 2, s12
	v_lshl_add_u32 v15, v15, 2, s12
	v_lshl_add_u32 v16, v16, 2, s12
	v_lshl_add_u32 v17, v17, 2, s12
	v_and_b32_e32 v18, 0xf80, v18
	v_and_b32_e32 v10, 0xfc0, v10
	v_lshl_add_u32 v18, v18, 2, s12
	v_lshl_add_u32 v19, v10, 2, s12
	ds_read_b32 v10, v12
	ds_read_b32 v11, v13
	ds_read_b32 v12, v14
	ds_read_b32 v13, v15
	ds_read_b32 v14, v16
	ds_read_b32 v15, v17
	ds_read_b32 v16, v18
	ds_read_b32 v17, v19
	s_waitcnt lgkmcnt(6)
	v_pk_mul_f32 v[10:11], v[10:11], s[0:1] op_sel_hi:[1,0]
	v_or_b32_e32 v101, 0x280, v95
	v_cvt_pk_bf16_f32 v70, v10, v11
	s_waitcnt lgkmcnt(4)
	v_pk_mul_f32 v[10:11], v[12:13], s[0:1] op_sel_hi:[1,0]
	v_or_b32_e32 v102, 0x2c0, v95
	v_cvt_pk_bf16_f32 v71, v10, v11
	s_waitcnt lgkmcnt(2)
	v_pk_mul_f32 v[10:11], v[14:15], s[0:1] op_sel_hi:[1,0]
	v_lshlrev_b32_e32 v88, 1, v2
	v_cvt_pk_bf16_f32 v72, v10, v11
	s_waitcnt lgkmcnt(0)
	v_pk_mul_f32 v[10:11], v[16:17], s[0:1] op_sel_hi:[1,0]
	s_cselect_b32 s0, 0, 0
	v_add3_u32 v3, v7, s0, v5
	v_cvt_pk_bf16_f32 v73, v10, v11
	v_add3_u32 v103, v3, v6, v9
	s_lshl_b32 s17, s33, 7
	s_mov_b32 s0, s2
	s_mov_b32 s18, 0
	s_waitcnt vmcnt(0)
	s_branch .LBB0_824

.LBB0_824:
	s_lshl_b32 s1, s18, 15
	s_add_i32 s10, s1, 0
	s_add_i32 s19, s0, s33
	s_cmpk_gt_i32 s19, 0x83f
	s_cselect_b64 s[12:13], -1, 0
	v_add_u32_e32 v2, s10, v92
	v_add_u32_e32 v3, s10, v93
	s_and_b64 vcc, exec, s[12:13]
	ds_write_b128 v2, v[62:65]
	ds_write_b128 v3, v[66:69]
	ds_write_b128 v2, v[74:77] offset:16384
	ds_write_b128 v3, v[78:81] offset:16384
	s_waitcnt lgkmcnt(0)
	s_barrier
	s_cbranch_vccnz .LBB0_826
	s_ashr_i32 s10, s19, 3
	s_mul_hi_i32 s14, s10, 0x3e0f83e1
	s_lshr_b32 s15, s14, 31
	s_ashr_i32 s14, s14, 3
	s_add_i32 s14, s14, s15
	s_lshl_b32 s15, s14, 6
	s_mul_i32 s14, s14, 33
	s_sub_i32 s10, s10, s14
	s_add_i32 s14, s15, s10
	s_ashr_i32 s15, s14, 31
	s_lshl_b64 s[14:15], s[14:15], 7
	v_mov_b32_e32 v3, s15
	v_or_b32_e32 v2, s14, v82
	s_add_i32 s10, s17, s16
	v_lshlrev_b64 v[2:3], 11, v[2:3]
	s_and_b32 s10, s10, 0x380
	v_mov_b32_e32 v5, s15
	v_or_b32_e32 v4, s14, v84
	v_lshl_add_u64 v[2:3], s[8:9], 0, v[2:3]
	s_lshl_b32 s10, s10, 1
	v_lshlrev_b64 v[4:5], 11, v[4:5]
	v_lshl_add_u64 v[2:3], v[2:3], 0, s[10:11]
	v_mov_b32_e32 v89, v87
	v_lshl_add_u64 v[4:5], s[8:9], 0, v[4:5]
	v_lshl_add_u64 v[2:3], v[2:3], 0, v[88:89]
	v_lshl_add_u64 v[4:5], v[4:5], 0, s[10:11]
	s_or_b32 s14, s14, 64
	v_lshl_add_u64 v[4:5], v[4:5], 0, v[88:89]
	global_load_dwordx4 v[62:65], v[2:3], off
	global_load_dwordx4 v[66:69], v[4:5], off
	v_mov_b32_e32 v3, s15
	v_or_b32_e32 v2, s14, v82
	v_lshlrev_b64 v[2:3], 11, v[2:3]
	v_lshl_add_u64 v[4:5], s[14:15], 0, v[84:85]
	v_lshl_add_u64 v[2:3], s[8:9], 0, v[2:3]
	v_lshlrev_b64 v[4:5], 11, v[4:5]
	v_lshl_add_u64 v[2:3], v[2:3], 0, s[10:11]
	v_lshl_add_u64 v[4:5], s[8:9], 0, v[4:5]
	v_lshl_add_u64 v[2:3], v[2:3], 0, v[88:89]
	v_lshl_add_u64 v[4:5], v[4:5], 0, s[10:11]
	v_lshl_add_u64 v[4:5], v[4:5], 0, v[88:89]
	global_load_dwordx4 v[74:77], v[2:3], off
	global_load_dwordx4 v[78:81], v[4:5], off
.LBB0_826:
	v_add_u32_e32 v86, s1, v103
	ds_read_b64_tr_b16 v[2:3], v86 offset:0
	ds_read_b64_tr_b16 v[4:5], v86 offset:0x800
	ds_read_b64_tr_b16 v[18:19], v86 offset:0x1000
	ds_read_b64_tr_b16 v[20:21], v86 offset:0x1800
	ds_read_b64_tr_b16 v[22:23], v86 offset:0x2000
	ds_read_b64_tr_b16 v[24:25], v86 offset:0x2800
	ds_read_b64_tr_b16 v[26:27], v86 offset:0x3000
	ds_read_b64_tr_b16 v[28:29], v86 offset:0x3800
	s_waitcnt lgkmcnt(0)
	s_nop 0
	v_mfma_f32_32x32x16_bf16 v[2:17], v[70:73], v[2:5], 0
	v_mfma_f32_32x32x16_bf16 v[2:17], v[58:61], v[18:21], v[2:17]
	ds_read_b64_tr_b16 v[18:19], v86 offset:0x200
	ds_read_b64_tr_b16 v[20:21], v86 offset:0xa00
	ds_read_b64_tr_b16 v[104:105], v86 offset:0x1200
	ds_read_b64_tr_b16 v[106:107], v86 offset:0x1a00
	ds_read_b64_tr_b16 v[108:109], v86 offset:0x2200
	ds_read_b64_tr_b16 v[110:111], v86 offset:0x2a00
	ds_read_b64_tr_b16 v[112:113], v86 offset:0x3200
	v_mfma_f32_32x32x16_bf16 v[2:17], v[54:57], v[22:25], v[2:17]
	ds_read_b64_tr_b16 v[114:115], v86 offset:0x3a00
	s_waitcnt lgkmcnt(0)
	v_mfma_f32_32x32x16_bf16 v[2:17], v[50:53], v[26:29], v[2:17]
	v_mfma_f32_32x32x16_bf16 v[18:33], v[70:73], v[18:21], 0
	v_add_u32_e32 v86, 0x4000, v86
	v_mfma_f32_32x32x16_bf16 v[18:33], v[58:61], v[104:107], v[18:33]
	ds_read_b64_tr_b16 v[104:105], v86 offset:0
	ds_read_b64_tr_b16 v[106:107], v86 offset:0x800
	v_mfma_f32_32x32x16_bf16 v[18:33], v[54:57], v[108:111], v[18:33]
	ds_read_b64_tr_b16 v[108:109], v86 offset:0x1000
	ds_read_b64_tr_b16 v[110:111], v86 offset:0x1800
	ds_read_b64_tr_b16 v[116:117], v86 offset:0x2000
	ds_read_b64_tr_b16 v[118:119], v86 offset:0x2800
	ds_read_b64_tr_b16 v[120:121], v86 offset:0x3000
	ds_read_b64_tr_b16 v[122:123], v86 offset:0x3800
	s_waitcnt lgkmcnt(0)
	v_mfma_f32_32x32x16_bf16 v[18:33], v[50:53], v[112:115], v[18:33]
	v_mfma_f32_32x32x16_bf16 v[2:17], v[46:49], v[104:107], v[2:17]
	ds_read_b64_tr_b16 v[104:105], v86 offset:0x200
	ds_read_b64_tr_b16 v[106:107], v86 offset:0xa00
	v_mfma_f32_32x32x16_bf16 v[2:17], v[42:45], v[108:111], v[2:17]
	ds_read_b64_tr_b16 v[108:109], v86 offset:0x1200
	ds_read_b64_tr_b16 v[110:111], v86 offset:0x1a00
	ds_read_b64_tr_b16 v[112:113], v86 offset:0x2200
	ds_read_b64_tr_b16 v[114:115], v86 offset:0x2a00
	v_mfma_f32_32x32x16_bf16 v[2:17], v[38:41], v[116:119], v[2:17]
	ds_read_b64_tr_b16 v[116:117], v86 offset:0x3200
	ds_read_b64_tr_b16 v[118:119], v86 offset:0x3a00
	s_waitcnt lgkmcnt(0)
	v_mfma_f32_32x32x16_bf16 v[2:17], v[34:37], v[120:123], v[2:17]
	v_mfma_f32_32x32x16_bf16 v[18:33], v[46:49], v[104:107], v[18:33]
	s_ashr_i32 s0, s0, 3
	s_mul_hi_i32 s1, s0, 0x3e0f83e1
	s_lshr_b32 s10, s1, 31
	s_ashr_i32 s1, s1, 3
	s_add_i32 s1, s1, s10
	s_mul_i32 s10, s1, 33
	s_sub_i32 s0, s0, s10
	v_mfma_f32_32x32x16_bf16 v[18:33], v[42:45], v[108:111], v[18:33]
	s_and_b32 s10, s0, 63
	s_and_b32 s14, s16, 0x380
	s_add_i32 s28, s10, -1
	s_cmp_lt_u32 s28, 31
	v_add_u32_e32 v86, s14, v94
	s_cselect_b64 s[14:15], -1, 0
	s_lshl_b32 s1, s1, 12
	v_mfma_f32_32x32x16_bf16 v[18:33], v[38:41], v[112:115], v[18:33]
	s_lshl_b32 s0, s0, 6
	s_add_i32 s1, s1, s0
	s_and_b32 s24, s1, 0xfffff000
	v_and_or_b32 v89, v86, s3, v83
	s_or_b32 s25, s24, s10
	v_lshlrev_b32_e32 v86, 2, v86
	v_and_b32_e32 v86, 0x1c00, v86
	v_mfma_f32_32x32x16_bf16 v[18:33], v[34:37], v[116:119], v[18:33]
	s_waitcnt vmcnt(0)
	v_or_b32_e32 v104, s25, v95
	v_lshl_add_u64 v[90:91], s[6:7], 0, v[86:87]
	v_lshlrev_b32_e32 v86, 1, v89
	v_ashrrev_i32_e32 v105, 31, v104
	s_addk_i32 s24, 0x1000
	v_lshl_add_u64 v[90:91], v[90:91], 0, v[86:87]
	v_lshlrev_b64 v[104:105], 12, v[104:105]
	s_cmp_gt_u32 s28, 30
	v_cvt_pk_bf16_f32 v2, v2, s0
	s_nop 2
	v_cvt_pk_bf16_f32 v18, v18, s0
	v_lshl_add_u64 v[104:105], v[90:91], 0, v[104:105]
	v_cvt_pk_bf16_f32 v10, v10, s0
	v_cvt_pk_bf16_f32 v26, v26, s0
	global_store_short v[104:105], v2, off
	global_store_short v[104:105], v18, off offset:64
	global_store_short v[104:105], v10, off offset:512
	global_store_short v[104:105], v26, off offset:576
	s_cbranch_scc1 .LBB0_828
	v_or_b32_e32 v86, s10, v95
	v_sub_u32_e32 v104, s24, v86
	v_ashrrev_i32_e32 v105, 31, v104
	v_lshlrev_b64 v[104:105], 12, v[104:105]
	v_lshl_add_u64 v[104:105], v[90:91], 0, v[104:105]
	v_xor_b32_e32 v26, 0x8000, v26
	v_xor_b32_e32 v10, 0x8000, v10
	global_store_short v[104:105], v2, off
	global_store_short v[104:105], v18, off offset:64
	global_store_short v[104:105], v10, off offset:512
	global_store_short v[104:105], v26, off offset:576
